# index phase: the two cross-half sums + v_cndmask per query pair merged into one permlane32_swap + one add (31 of 40 sites), bit-exact
# speedup vs baseline: 1.0144x; 1.0144x over previous
; #define MFMA32(a, b, c) __builtin_amdgcn_mfma_f32_32x32x16_bf16((a), (b), (c), 0, 0, 0)
; DI float xhalf_sum(float v) { const auto r = __builtin_amdgcn_permlane32_swap(__float_as_uint(v), __float_as_uint(v), false, false); return __uint_as_float(r[0]) + __uint_as_float(r[1]); }
; DI void phase_index(const Params& p, unsigned char* lds) {
;     ...
;         auto mma = [&](f32x16& s, unsigned off) {
; #pragma unroll
;             for (int i = 0; i < 16; ++i) s[i] = 0.f;
; #pragma unroll
;             for (int ks = 0; ks < 4; ++ks) { const bf16x8 kf = *(const bf16x8*)(lds + off + ks * 32); s = MFMA32(qf[ks], kf, s); }
;         };
;         auto proc = [&](auto PASSC, auto DIAGC, const f32x16& s, int k0, int kb) {
;             constexpr int PASS = decltype(PASSC)::value; constexpr bool DIAG = decltype(DIAGC)::value != 0;
;             f32x4 tot;
; #pragma unroll
;             for (int q = 0; q < 4; ++q) {
;                 float pr = 0.f;
; #pragma unroll
;                 for (int e = 0; e < 4; ++e) pr += wq[q][e] * fmaxf(s[4 * q + e], 0.f);
;                 tot[q] = xhalf_sum(pr);
;             }
;             const int key = k0 + 32 * kb + r32;
; #pragma unroll
;             for (int qq = 0; qq < 2; ++qq) {
;                 const float t_lo = tot[qq], t_hi = tot[2 + qq];
;                 const float sc = ((lane & 32) ? t_hi : t_lo) + 0.0f;
;                 const unsigned ub = __float_as_uint(sc);
;                 const unsigned uk = ub ^ ((unsigned)((int)ub >> 31) | 0x80000000u);
;                 const bool valid = DIAG ? (key <= tq0 + qq) : true;
;                 if (PASS == 0) {
;                     if (valid) { const unsigned a = (uk >> 21) & 0x7feu; atomicAdd((unsigned*)(lds + hbase0 + qq * 2048 + (a & ~3u)), 1u << ((a & 2u) << 3)); }
.LBB0_2567:
	s_bitcmp1_b32 s28, 0
	s_cselect_b32 s34, 0x9000, 0
	v_add_u32_e32 v106, s34, v154
	ds_read_b128 v[2:5], v106
	ds_read_b128 v[6:9], v106 offset:32
	s_cmp_lg_u32 s0, 0
	s_cselect_b64 s[28:29], -1, 0
	s_and_b64 vcc, exec, s[28:29]
	s_waitcnt lgkmcnt(1)
	v_mfma_f32_32x32x16_bf16 v[18:33], v[42:45], v[2:5], 0
	ds_read_b128 v[2:5], v106 offset:64
	ds_read_b128 v[102:105], v106 offset:96
	s_waitcnt lgkmcnt(2)
	v_mfma_f32_32x32x16_bf16 v[18:33], v[34:37], v[6:9], v[18:33]
	s_waitcnt lgkmcnt(1)
	v_mfma_f32_32x32x16_bf16 v[18:33], v[38:41], v[2:5], v[18:33]
	ds_read_b128 v[2:5], v106 offset:4608
	ds_read_b128 v[108:111], v106 offset:4640
	s_waitcnt lgkmcnt(2)
	v_mfma_f32_32x32x16_bf16 v[18:33], v[46:49], v[102:105], v[18:33]
	s_waitcnt lgkmcnt(1)
	v_mfma_f32_32x32x16_bf16 v[2:17], v[42:45], v[2:5], 0
	s_nop 9
	v_max_f32_e32 v18, 0, v18
	v_max_f32_e32 v103, 0, v21
	v_max_f32_e32 v21, 0, v22
	v_max_f32_e32 v102, 0, v20
	v_max_f32_e32 v22, 0, v23
	v_fma_f32 v20, v50, v18, 0
	v_fma_f32 v18, v54, v21, 0
	s_waitcnt lgkmcnt(0)
	v_mfma_f32_32x32x16_bf16 v[2:17], v[34:37], v[108:111], v[2:17]
	v_max_f32_e32 v23, 0, v24
	v_fmac_f32_e32 v18, v55, v22
	v_max_f32_e32 v24, 0, v25
	v_max_f32_e32 v25, 0, v26
	v_fmac_f32_e32 v18, v56, v23
	v_fma_f32 v21, v58, v25, 0
	v_fmac_f32_e32 v18, v57, v24
	ds_read_b128 v[22:25], v106 offset:4672
	v_max_f32_e32 v19, 0, v19
	v_max_f32_e32 v26, 0, v27
	v_max_f32_e32 v27, 0, v28
	v_fmac_f32_e32 v20, v51, v19
	v_fmac_f32_e32 v21, v59, v26
	v_fmac_f32_e32 v21, v60, v27
	v_max_f32_e32 v19, 0, v29
	v_fmac_f32_e32 v21, v61, v19
	v_max_f32_e32 v19, v30, v30
	v_max_f32_e32 v30, 0, v31
	ds_read_b128 v[26:29], v106 offset:4704
	s_waitcnt lgkmcnt(1)
	v_mfma_f32_32x32x16_bf16 v[2:17], v[38:41], v[22:25], v[2:17]
	v_max_f32_e32 v19, 0, v19
	v_fma_f32 v19, v62, v19, 0
	v_fmac_f32_e32 v19, v63, v30
	v_max_f32_e32 v22, 0, v32
	v_fmac_f32_e32 v19, v64, v22
	s_waitcnt lgkmcnt(0)
	v_mfma_f32_32x32x16_bf16 v[2:17], v[46:49], v[26:29], v[2:17]
	v_fmac_f32_e32 v20, v52, v102
	v_max_f32_e32 v22, 0, v33
	v_fmac_f32_e32 v20, v53, v103
	v_fmac_f32_e32 v19, v65, v22
	s_cbranch_vccz .LBB0_2575
	v_mov_b32_e32 v22, v20
	s_nop 1
	v_mov_b32_e32 v23, v18
	s_nop 1
	v_mov_b32_e32 v24, v21
	s_nop 1
	v_permlane32_swap_b32_e32 v22, v24
	v_add_f32_e32 v22, v22, v24
	v_add_f32_e32 v22, 0, v22
	v_ashrrev_i32_e32 v24, 31, v22
	v_bitop3_b32 v22, v24, v22, s82 bitop3:0x36
	v_lshrrev_b32_e32 v24, 21, v22
	v_lshrrev_b32_e32 v22, 18, v22
	v_and_b32_e32 v24, 0x7fc, v24
	v_and_b32_e32 v22, 16, v22
	v_add_u32_e32 v24, v123, v24
	v_lshlrev_b32_e64 v22, v22, 1
	ds_add_u32 v24, v22
	v_mov_b32_e32 v25, v19
	s_nop 1
	v_permlane32_swap_b32_e32 v23, v25
	v_add_f32_e32 v22, v23, v25
	s_mov_b64 s[30:31], -1
	s_cbranch_execz .LBB0_2576
	s_and_saveexec_b64 s[50:51], s[30:31]
	s_cbranch_execz .LBB0_2571

; DI float xhalf_sum(float v) { const auto r = __builtin_amdgcn_permlane32_swap(__float_as_uint(v), __float_as_uint(v), false, false); return __uint_as_float(r[0]) + __uint_as_float(r[1]); }
; DI void phase_index(const Params& p, unsigned char* lds) {
;     ...
;             for (int q = 0; q < 4; ++q) {
;                 float pr = 0.f;
; #pragma unroll
;                 for (int e = 0; e < 4; ++e) pr += wq[q][e] * fmaxf(s[4 * q + e], 0.f);
;                 tot[q] = xhalf_sum(pr);
;             }
;             const int key = k0 + 32 * kb + r32;
; #pragma unroll
;             for (int qq = 0; qq < 2; ++qq) {
;                 const float t_lo = tot[qq], t_hi = tot[2 + qq];
;                 const float sc = ((lane & 32) ? t_hi : t_lo) + 0.0f;
;                 const unsigned ub = __float_as_uint(sc);
;                 const unsigned uk = ub ^ ((unsigned)((int)ub >> 31) | 0x80000000u);
;                 const bool valid = DIAG ? (key <= tq0 + qq) : true;
;                 if (PASS == 0) {
;                     if (valid) { const unsigned a = (uk >> 21) & 0x7feu; atomicAdd((unsigned*)(lds + hbase0 + qq * 2048 + (a & ~3u)), 1u << ((a & 2u) << 3)); }
.LBB0_2571:
	s_or_b64 exec, exec, s[50:51]
	v_max_f32_e32 v2, 0, v2
	v_fma_f32 v2, v50, v2, 0
	v_max_f32_e32 v3, 0, v3
	v_fmac_f32_e32 v2, v51, v3
	v_max_f32_e32 v3, 0, v4
	v_fmac_f32_e32 v2, v52, v3
	v_max_f32_e32 v3, 0, v5
	v_fmac_f32_e32 v2, v53, v3
	s_and_b64 vcc, exec, s[28:29]
	v_max_f32_e32 v21, v6, v6
	v_max_f32_e32 v20, v7, v7
	v_max_f32_e32 v19, v8, v8
	v_max_f32_e32 v18, v9, v9
	v_max_f32_e32 v10, v10, v10
	v_max_f32_e32 v9, v11, v11
	v_max_f32_e32 v8, v12, v12
	v_max_f32_e32 v7, v13, v13
	v_max_f32_e32 v6, v14, v14
	v_max_f32_e32 v5, v15, v15
	v_max_f32_e32 v4, v16, v16
	v_max_f32_e32 v3, v17, v17
	s_cbranch_vccz .LBB0_2581
	v_mov_b32_e32 v11, v2
	s_nop 1
	v_max_f32_e32 v12, 0, v21
	v_max_f32_e32 v13, 0, v20
	v_pk_mul_f32 v[12:13], v[54:55], v[12:13]
	s_nop 0
	v_add_f32_e32 v12, 0, v12
	v_add_f32_e32 v14, v13, v12
	v_max_f32_e32 v12, 0, v19
	v_max_f32_e32 v13, 0, v18
	v_pk_mul_f32 v[12:13], v[56:57], v[12:13]
	s_mov_b64 s[28:29], -1
	v_add_f32_e32 v12, v12, v14
	v_add_f32_e32 v12, v13, v12
	v_mov_b32_e32 v13, v12
	s_nop 1
	v_permlane32_swap_b32_e32 v12, v13
	v_add_f32_e32 v14, v12, v13
	v_max_f32_e32 v12, 0, v10
	v_fma_f32 v12, v58, v12, 0
	v_max_f32_e32 v13, 0, v9
	v_fmac_f32_e32 v12, v59, v13
	v_max_f32_e32 v13, 0, v8
	v_fmac_f32_e32 v12, v60, v13
	v_max_f32_e32 v13, 0, v7
	v_fmac_f32_e32 v12, v61, v13
	s_nop 1
	v_permlane32_swap_b32_e32 v11, v12
	v_add_f32_e32 v11, v11, v12
	v_max_f32_e32 v12, 0, v6
	v_max_f32_e32 v13, 0, v5
	v_add_f32_e32 v11, 0, v11
	v_pk_mul_f32 v[12:13], v[62:63], v[12:13]
	v_ashrrev_i32_e32 v15, 31, v11
	v_add_f32_e32 v12, 0, v12
	v_bitop3_b32 v11, v15, v11, s82 bitop3:0x36
	v_add_f32_e32 v16, v13, v12
	v_max_f32_e32 v12, 0, v4
	v_max_f32_e32 v13, 0, v3
	v_lshrrev_b32_e32 v15, 21, v11
	v_lshrrev_b32_e32 v11, 18, v11
	v_pk_mul_f32 v[12:13], v[64:65], v[12:13]
	v_and_b32_e32 v15, 0x7fc, v15
	v_and_b32_e32 v11, 16, v11
	v_add_f32_e32 v12, v12, v16
	v_add_u32_e32 v15, v123, v15
	v_lshlrev_b32_e64 v11, v11, 1
	v_add_f32_e32 v12, v13, v12
	ds_add_u32 v15, v11
	v_mov_b32_e32 v13, v12
	s_nop 1
	v_permlane32_swap_b32_e32 v12, v13
	v_add_f32_e32 v11, v12, v13
	v_cndmask_b32_e64 v13, v11, v14, s[4:5]
	s_cbranch_execz .LBB0_2582
	s_and_saveexec_b64 s[30:31], s[28:29]
	s_cbranch_execnz .LBB0_2587

; DI void phase_index(const Params& p, unsigned char* lds) {
;     ...
;             const int key = k0 + 32 * kb + r32;
; #pragma unroll
;             for (int qq = 0; qq < 2; ++qq) {
;                 const float t_lo = tot[qq], t_hi = tot[2 + qq];
;                 const float sc = ((lane & 32) ? t_hi : t_lo) + 0.0f;
;                 const unsigned ub = __float_as_uint(sc);
;                 const unsigned uk = ub ^ ((unsigned)((int)ub >> 31) | 0x80000000u);
;                 const bool valid = DIAG ? (key <= tq0 + qq) : true;
;                 if (PASS == 0) {
;                     if (valid) { const unsigned a = (uk >> 21) & 0x7feu; atomicAdd((unsigned*)(lds + hbase0 + qq * 2048 + (a & ~3u)), 1u << ((a & 2u) << 3)); }
.LBB0_2576:
	v_permlane32_swap_b32_e32 v20, v21
	v_permlane32_swap_b32_e32 v18, v19
	v_cmp_le_i32_e32 vcc, v83, v95
	s_and_saveexec_b64 s[50:51], vcc
	s_cbranch_execz .LBB0_2578
	v_add_f32_e32 v20, v20, v21
	v_add_f32_e32 v20, 0, v20
	v_ashrrev_i32_e32 v21, 31, v20
	v_bitop3_b32 v20, v21, v20, s82 bitop3:0x36
	v_lshrrev_b32_e32 v21, 21, v20
	v_lshrrev_b32_e32 v20, 18, v20
	v_and_b32_e32 v21, 0x7fc, v21
	v_and_b32_e32 v20, 16, v20
	v_add_u32_e32 v21, v123, v21
	v_lshlrev_b32_e64 v20, v20, 1
	ds_add_u32 v21, v20
.LBB0_2578:
	s_or_b64 exec, exec, s[50:51]
	v_cmp_le_i32_e32 vcc, v83, v1
	s_and_saveexec_b64 s[50:51], vcc
	v_add_f32_e32 v22, v18, v19
	s_or_b64 s[30:31], s[30:31], exec
	s_or_b64 exec, exec, s[50:51]
	s_and_saveexec_b64 s[50:51], s[30:31]
	s_cbranch_execnz .LBB0_2570
	s_branch .LBB0_2571

; DI void phase_index(const Params& p, unsigned char* lds) {
;     ...
;             const int key = k0 + 32 * kb + r32;
; #pragma unroll
;             for (int qq = 0; qq < 2; ++qq) {
;                 const float t_lo = tot[qq], t_hi = tot[2 + qq];
;                 const float sc = ((lane & 32) ? t_hi : t_lo) + 0.0f;
;                 const unsigned ub = __float_as_uint(sc);
;                 const unsigned uk = ub ^ ((unsigned)((int)ub >> 31) | 0x80000000u);
;                 const bool valid = DIAG ? (key <= tq0 + qq) : true;
;                 if (PASS == 0) {
;                     if (valid) { const unsigned a = (uk >> 21) & 0x7feu; atomicAdd((unsigned*)(lds + hbase0 + qq * 2048 + (a & ~3u)), 1u << ((a & 2u) << 3)); }
.LBB0_2582:
	v_max_f32_e32 v11, 0, v21
	v_max_f32_e32 v10, 0, v10
	v_max_f32_e32 v6, 0, v6
	v_fma_f32 v11, v54, v11, 0
	v_max_f32_e32 v12, 0, v20
	v_fma_f32 v10, v58, v10, 0
	v_max_f32_e32 v9, 0, v9
	v_fma_f32 v6, v62, v6, 0
	v_max_f32_e32 v5, 0, v5
	v_fmac_f32_e32 v11, v55, v12
	v_max_f32_e32 v12, 0, v19
	v_fmac_f32_e32 v10, v59, v9
	v_max_f32_e32 v8, 0, v8
	v_fmac_f32_e32 v6, v63, v5
	v_max_f32_e32 v4, 0, v4
	v_fmac_f32_e32 v11, v56, v12
	v_max_f32_e32 v12, 0, v18
	v_fmac_f32_e32 v10, v60, v8
	v_max_f32_e32 v7, 0, v7
	v_fmac_f32_e32 v6, v64, v4
	v_max_f32_e32 v3, 0, v3
	v_fmac_f32_e32 v11, v57, v12
	v_fmac_f32_e32 v10, v61, v7
	v_fmac_f32_e32 v6, v65, v3
	v_add_u32_e32 v4, 32, v83
	v_permlane32_swap_b32_e32 v2, v10
	v_permlane32_swap_b32_e32 v11, v6
	v_cmp_le_i32_e32 vcc, v4, v95
	s_and_saveexec_b64 s[30:31], vcc
	s_cbranch_execz .LBB0_2584
	v_add_f32_e32 v2, v2, v10
	v_add_f32_e32 v2, 0, v2
	v_ashrrev_i32_e32 v4, 31, v2
	v_bitop3_b32 v2, v4, v2, s82 bitop3:0x36
	v_lshrrev_b32_e32 v4, 21, v2
	v_lshrrev_b32_e32 v2, 18, v2
	v_and_b32_e32 v4, 0x7fc, v4
	v_and_b32_e32 v2, 16, v2
	v_add_u32_e32 v4, v123, v4
	v_lshlrev_b32_e64 v2, v2, 1
	ds_add_u32 v4, v2
.LBB0_2584:
	s_or_b64 exec, exec, s[30:31]
	v_add_u32_e32 v2, 31, v83
	v_cmp_le_i32_e32 vcc, v2, v95
	s_and_saveexec_b64 s[30:31], vcc
	v_add_f32_e32 v13, v11, v6
	s_or_b64 s[28:29], s[28:29], exec
	s_or_b64 exec, exec, s[30:31]
	s_and_saveexec_b64 s[30:31], s[28:29]
	s_cbranch_execz .LBB0_2574

; DI float xhalf_sum(float v) { const auto r = __builtin_amdgcn_permlane32_swap(__float_as_uint(v), __float_as_uint(v), false, false); return __uint_as_float(r[0]) + __uint_as_float(r[1]); }
; DI void phase_index(const Params& p, unsigned char* lds) {
;     ...
;             for (int q = 0; q < 4; ++q) {
;                 float pr = 0.f;
; #pragma unroll
;                 for (int e = 0; e < 4; ++e) pr += wq[q][e] * fmaxf(s[4 * q + e], 0.f);
;                 tot[q] = xhalf_sum(pr);
;             }
;             const int key = k0 + 32 * kb + r32;
; #pragma unroll
;             for (int qq = 0; qq < 2; ++qq) {
;                 const float t_lo = tot[qq], t_hi = tot[2 + qq];
;                 const float sc = ((lane & 32) ? t_hi : t_lo) + 0.0f;
;                 const unsigned ub = __float_as_uint(sc);
;                 const unsigned uk = ub ^ ((unsigned)((int)ub >> 31) | 0x80000000u);
;                 const bool valid = DIAG ? (key <= tq0 + qq) : true;
;                 if (PASS == 0) {
;                     if (valid) { const unsigned a = (uk >> 21) & 0x7feu; atomicAdd((unsigned*)(lds + hbase0 + qq * 2048 + (a & ~3u)), 1u << ((a & 2u) << 3)); }
;                 } else if (PASS == 1) {
;                     if (valid && (int)(uk >> 22) == b1v[qq]) { const unsigned a = (uk >> 11) & 0x7feu; atomicAdd((unsigned*)(lds + hbase0 + qq * 2048 + (a & ~3u)), 1u << ((a & 2u) << 3)); }
;                 } else if (PASS == 3) {
;                     if (valid) {
;                         const int k10 = (int)(uk >> 22), d = k10 - b1v[qq];
;                         if (k10 > hiv[qq]) cntA[qq] += 1;
;                         else if (d >= 0) {
;                             const unsigned bin = ((unsigned)d << sbv[qq]) | ((uk >> (22 - sbv[qq])) & ((1u << sbv[qq]) - 1u));
;                             const unsigned a = bin << 1;
;                             atomicAdd((unsigned*)(lds + hbase0 + qq * 2048 + (a & ~3u)), 1u << ((a & 2u) << 3));
;                         }
;                     }
.LBB0_2639:
	v_max_f32_e32 v18, 0, v18
	v_fma_f32 v168, v50, v18, 0
	v_max_f32_e32 v18, 0, v19
	v_fmac_f32_e32 v168, v51, v18
	v_max_f32_e32 v18, 0, v20
	v_fmac_f32_e32 v168, v52, v18
	v_max_f32_e32 v18, 0, v21
	v_fmac_f32_e32 v168, v53, v18
	v_max_f32_e32 v18, 0, v22
	v_fma_f32 v18, v54, v18, 0
	v_max_f32_e32 v19, 0, v23
	v_fmac_f32_e32 v18, v55, v19
	v_max_f32_e32 v19, 0, v24
	v_fmac_f32_e32 v18, v56, v19
	v_max_f32_e32 v19, 0, v25
	v_fmac_f32_e32 v18, v57, v19
	v_max_f32_e32 v19, 0, v26
	v_fma_f32 v20, v58, v19, 0
	v_max_f32_e32 v19, 0, v27
	v_fmac_f32_e32 v20, v59, v19
	v_max_f32_e32 v19, 0, v28
	v_fmac_f32_e32 v20, v60, v19
	v_max_f32_e32 v19, 0, v29
	v_fmac_f32_e32 v20, v61, v19
	v_max_f32_e32 v19, 0, v30
	v_fma_f32 v19, v62, v19, 0
	v_max_f32_e32 v21, 0, v31
	v_fmac_f32_e32 v19, v63, v21
	v_max_f32_e32 v21, 0, v32
	v_fmac_f32_e32 v19, v64, v21
	v_max_f32_e32 v21, 0, v33
	v_fmac_f32_e32 v19, v65, v21
	s_mov_b64 s[30:31], -1
	s_and_b64 vcc, exec, s[28:29]
	s_cbranch_vccz .LBB0_2653
	v_mov_b32_e32 v21, v168
	v_mov_b32_e32 v23, v20
	s_nop 0
	s_nop 0
	v_permlane32_swap_b32_e32 v21, v23
	v_add_f32_e32 v25, v21, v23
	v_add_f32_e32 v25, 0, v25
	v_ashrrev_i32_e32 v26, 31, v25
	v_bitop3_b32 v25, v26, v25, s82 bitop3:0x36
	v_mov_b32_e32 v21, v18
	v_mov_b32_e32 v23, v19
	v_lshrrev_b32_e32 v26, 22, v25
	s_nop 0
	v_permlane32_swap_b32_e32 v21, v23
	v_cmp_le_i32_e32 vcc, v26, v101
	s_and_saveexec_b64 s[28:29], vcc
	s_xor_b64 s[28:29], exec, s[28:29]
	s_cbranch_execz .LBB0_2644
	v_sub_u32_e32 v26, v26, v100
	v_cmp_lt_i32_e32 vcc, -1, v26
	s_and_saveexec_b64 s[30:31], vcc
	s_cbranch_execz .LBB0_2643
	v_lshrrev_b32_e32 v25, v113, v25
	v_and_b32_e32 v25, v25, v114
	v_lshl_or_b32 v25, v26, v111, v25
	v_lshlrev_b32_e32 v26, 1, v25
	v_and_b32_e32 v26, -4, v26
	v_lshlrev_b32_e32 v25, 4, v25
	v_add_u32_e32 v26, v123, v26
	v_lshlrev_b32_e64 v25, v25, 1
	ds_add_u32 v26, v25

; DI void phase_index(const Params& p, unsigned char* lds) {
;     ...
;                 } else if (PASS == 3) {
;                     if (valid) {
;                         const int k10 = (int)(uk >> 22), d = k10 - b1v[qq];
;                         if (k10 > hiv[qq]) cntA[qq] += 1;
;                         else if (d >= 0) {
;                             const unsigned bin = ((unsigned)d << sbv[qq]) | ((uk >> (22 - sbv[qq])) & ((1u << sbv[qq]) - 1u));
;                             const unsigned a = bin << 1;
;                             atomicAdd((unsigned*)(lds + hbase0 + qq * 2048 + (a & ~3u)), 1u << ((a & 2u) << 3));
;                         }
;                     }
.LBB0_2644:
	s_or_saveexec_b64 s[28:29], s[28:29]
	v_mov_b32_e32 v165, v167
	s_xor_b64 exec, exec, s[28:29]
	v_add_u32_e32 v165, 1, v167
	s_or_b64 exec, exec, s[28:29]
	v_add_f32_e32 v21, v21, v23
	v_add_f32_e32 v21, 0, v21
	v_ashrrev_i32_e32 v22, 31, v21
	v_bitop3_b32 v21, v22, v21, s82 bitop3:0x36
	v_lshrrev_b32_e32 v22, 22, v21
	v_cmp_le_i32_e32 vcc, v22, v103
	s_and_saveexec_b64 s[28:29], vcc
	s_xor_b64 s[28:29], exec, s[28:29]
	s_cbranch_execz .LBB0_2650
	v_sub_u32_e32 v22, v22, v102
	v_cmp_lt_i32_e32 vcc, -1, v22
	s_and_saveexec_b64 s[30:31], vcc
	s_cbranch_execz .LBB0_2649
	v_lshrrev_b32_e32 v21, v115, v21
	v_and_b32_e32 v21, v21, v116
	v_lshl_or_b32 v21, v22, v112, v21
	v_lshlrev_b32_e32 v22, 1, v21
	v_and_b32_e32 v22, -4, v22
	v_lshlrev_b32_e32 v21, 4, v21
	v_add_u32_e32 v22, v123, v22
	v_lshlrev_b32_e64 v21, v21, 1
	ds_add_u32 v22, v21 offset:2048

; DI void phase_index(const Params& p, unsigned char* lds) {
;     ...
;             const int key = k0 + 32 * kb + r32;
; #pragma unroll
;             for (int qq = 0; qq < 2; ++qq) {
;                 const float t_lo = tot[qq], t_hi = tot[2 + qq];
;                 const float sc = ((lane & 32) ? t_hi : t_lo) + 0.0f;
;                 const unsigned ub = __float_as_uint(sc);
;                 const unsigned uk = ub ^ ((unsigned)((int)ub >> 31) | 0x80000000u);
;                 const bool valid = DIAG ? (key <= tq0 + qq) : true;
;                 if (PASS == 0) {
;                     if (valid) { const unsigned a = (uk >> 21) & 0x7feu; atomicAdd((unsigned*)(lds + hbase0 + qq * 2048 + (a & ~3u)), 1u << ((a & 2u) << 3)); }
;                 } else if (PASS == 1) {
;                     if (valid && (int)(uk >> 22) == b1v[qq]) { const unsigned a = (uk >> 11) & 0x7feu; atomicAdd((unsigned*)(lds + hbase0 + qq * 2048 + (a & ~3u)), 1u << ((a & 2u) << 3)); }
;                 } else if (PASS == 3) {
;                     if (valid) {
;                         const int k10 = (int)(uk >> 22), d = k10 - b1v[qq];
;                         if (k10 > hiv[qq]) cntA[qq] += 1;
;                         else if (d >= 0) {
;                             const unsigned bin = ((unsigned)d << sbv[qq]) | ((uk >> (22 - sbv[qq])) & ((1u << sbv[qq]) - 1u));
;                             const unsigned a = bin << 1;
;                             atomicAdd((unsigned*)(lds + hbase0 + qq * 2048 + (a & ~3u)), 1u << ((a & 2u) << 3));
;                         }
;                     }
.LBB0_2653:
	s_and_b64 vcc, exec, s[30:31]
	s_cbranch_vccz .LBB0_2634
	v_add_u32_e32 v25, 32, v164
	v_permlane32_swap_b32_e32 v168, v20
	v_permlane32_swap_b32_e32 v18, v19
	v_cmp_le_i32_e32 vcc, v25, v95
	s_and_saveexec_b64 s[28:29], vcc
	s_cbranch_execz .LBB0_2662
	v_add_f32_e32 v20, v168, v20
	v_add_f32_e32 v20, 0, v20
	v_ashrrev_i32_e32 v23, 31, v20
	v_bitop3_b32 v20, v23, v20, s82 bitop3:0x36
	v_lshrrev_b32_e32 v23, 22, v20
	v_cmp_le_i32_e32 vcc, v23, v101
	s_and_saveexec_b64 s[30:31], vcc
	s_xor_b64 s[30:31], exec, s[30:31]
	s_cbranch_execz .LBB0_2659
	v_sub_u32_e32 v23, v23, v100
	v_cmp_lt_i32_e32 vcc, -1, v23
	s_and_saveexec_b64 s[38:39], vcc
	s_cbranch_execz .LBB0_2658
	v_lshrrev_b32_e32 v20, v113, v20
	v_and_b32_e32 v20, v20, v114
	v_lshl_or_b32 v20, v23, v111, v20
	v_lshlrev_b32_e32 v23, 1, v20
	v_and_b32_e32 v23, -4, v23
	v_lshlrev_b32_e32 v20, 4, v20
	v_add_u32_e32 v23, v123, v23
	v_lshlrev_b32_e64 v20, v20, 1
	ds_add_u32 v23, v20

; DI void phase_index(const Params& p, unsigned char* lds) {
;     ...
;                 } else if (PASS == 3) {
;                     if (valid) {
;                         const int k10 = (int)(uk >> 22), d = k10 - b1v[qq];
;                         if (k10 > hiv[qq]) cntA[qq] += 1;
;                         else if (d >= 0) {
;                             const unsigned bin = ((unsigned)d << sbv[qq]) | ((uk >> (22 - sbv[qq])) & ((1u << sbv[qq]) - 1u));
;                             const unsigned a = bin << 1;
;                             atomicAdd((unsigned*)(lds + hbase0 + qq * 2048 + (a & ~3u)), 1u << ((a & 2u) << 3));
;                         }
;                     }
.LBB0_2662:
	s_or_b64 exec, exec, s[28:29]
	v_add_u32_e32 v20, 31, v164
	v_cmp_le_i32_e32 vcc, v20, v95
	s_and_saveexec_b64 s[28:29], vcc
	s_cbranch_execz .LBB0_2633
	v_add_f32_e32 v18, v18, v19
	v_add_f32_e32 v18, 0, v18
	v_ashrrev_i32_e32 v19, 31, v18
	v_bitop3_b32 v18, v19, v18, s82 bitop3:0x36
	v_lshrrev_b32_e32 v19, 22, v18
	v_cmp_le_i32_e32 vcc, v19, v103
	s_and_saveexec_b64 s[30:31], vcc
	s_xor_b64 s[30:31], exec, s[30:31]
	s_cbranch_execz .LBB0_2667
	v_sub_u32_e32 v19, v19, v102
	v_cmp_lt_i32_e32 vcc, -1, v19
	s_and_saveexec_b64 s[38:39], vcc
	s_cbranch_execz .LBB0_2666
	v_lshrrev_b32_e32 v18, v115, v18
	v_and_b32_e32 v18, v18, v116
	v_lshl_or_b32 v18, v19, v112, v18
	v_lshlrev_b32_e32 v19, 1, v18
	v_and_b32_e32 v19, -4, v19
	v_lshlrev_b32_e32 v18, 4, v18
	v_add_u32_e32 v19, v123, v19
	v_lshlrev_b32_e64 v18, v18, 1
	ds_add_u32 v19, v18 offset:2048

; DI float xhalf_sum(float v) { const auto r = __builtin_amdgcn_permlane32_swap(__float_as_uint(v), __float_as_uint(v), false, false); return __uint_as_float(r[0]) + __uint_as_float(r[1]); }
; DI void phase_index(const Params& p, unsigned char* lds) {
;     ...
;             for (int q = 0; q < 4; ++q) {
;                 float pr = 0.f;
; #pragma unroll
;                 for (int e = 0; e < 4; ++e) pr += wq[q][e] * fmaxf(s[4 * q + e], 0.f);
;                 tot[q] = xhalf_sum(pr);
;             }
;             const int key = k0 + 32 * kb + r32;
; #pragma unroll
;             for (int qq = 0; qq < 2; ++qq) {
;                 const float t_lo = tot[qq], t_hi = tot[2 + qq];
;                 const float sc = ((lane & 32) ? t_hi : t_lo) + 0.0f;
;                 const unsigned ub = __float_as_uint(sc);
;                 const unsigned uk = ub ^ ((unsigned)((int)ub >> 31) | 0x80000000u);
;                 const bool valid = DIAG ? (key <= tq0 + qq) : true;
;                 if (PASS == 0) {
;                     if (valid) { const unsigned a = (uk >> 21) & 0x7feu; atomicAdd((unsigned*)(lds + hbase0 + qq * 2048 + (a & ~3u)), 1u << ((a & 2u) << 3)); }
;                 } else if (PASS == 1) {
;                     if (valid && (int)(uk >> 22) == b1v[qq]) { const unsigned a = (uk >> 11) & 0x7feu; atomicAdd((unsigned*)(lds + hbase0 + qq * 2048 + (a & ~3u)), 1u << ((a & 2u) << 3)); }
;                 } else if (PASS == 3) {
;                     if (valid) {
;                         const int k10 = (int)(uk >> 22), d = k10 - b1v[qq];
;                         if (k10 > hiv[qq]) cntA[qq] += 1;
;                         else if (d >= 0) {
;                             const unsigned bin = ((unsigned)d << sbv[qq]) | ((uk >> (22 - sbv[qq])) & ((1u << sbv[qq]) - 1u));
;                             const unsigned a = bin << 1;
;                             atomicAdd((unsigned*)(lds + hbase0 + qq * 2048 + (a & ~3u)), 1u << ((a & 2u) << 3));
;                         }
;                     }
.LBB0_2669:
	v_mov_b32_e32 v167, v173
	v_mov_b32_e32 v176, v174
	s_nop 0
	s_nop 0
	v_permlane32_swap_b32_e32 v167, v176
	v_add_f32_e32 v167, v167, v176
	v_add_f32_e32 v167, 0, v167
	v_ashrrev_i32_e32 v178, 31, v167
	v_bitop3_b32 v167, v178, v167, s82 bitop3:0x36
	v_mov_b32_e32 v169, v170
	v_mov_b32_e32 v176, v172
	v_lshrrev_b32_e32 v178, 22, v167
	s_nop 0
	v_permlane32_swap_b32_e32 v169, v176
	v_cmp_le_i32_e32 vcc, v178, v101
	s_and_saveexec_b64 s[30:31], vcc
	s_xor_b64 s[30:31], exec, s[30:31]
	s_cbranch_execz .LBB0_2673
	v_sub_u32_e32 v178, v178, v100
	v_cmp_lt_i32_e32 vcc, -1, v178
	s_and_saveexec_b64 s[38:39], vcc
	s_cbranch_execz .LBB0_2672
	v_lshrrev_b32_e32 v167, v113, v167
	v_and_b32_e32 v167, v167, v114
	v_lshl_or_b32 v167, v178, v111, v167
	v_lshlrev_b32_e32 v178, 1, v167
	v_and_b32_e32 v178, -4, v178
	v_lshlrev_b32_e32 v167, 4, v167
	v_add_u32_e32 v178, v123, v178
	v_lshlrev_b32_e64 v167, v167, 1
	ds_add_u32 v178, v167

; DI void phase_index(const Params& p, unsigned char* lds) {
;     ...
;                 } else if (PASS == 3) {
;                     if (valid) {
;                         const int k10 = (int)(uk >> 22), d = k10 - b1v[qq];
;                         if (k10 > hiv[qq]) cntA[qq] += 1;
;                         else if (d >= 0) {
;                             const unsigned bin = ((unsigned)d << sbv[qq]) | ((uk >> (22 - sbv[qq])) & ((1u << sbv[qq]) - 1u));
;                             const unsigned a = bin << 1;
;                             atomicAdd((unsigned*)(lds + hbase0 + qq * 2048 + (a & ~3u)), 1u << ((a & 2u) << 3));
;                         }
;                     }
.LBB0_2673:
	s_or_saveexec_b64 s[30:31], s[30:31]
	v_mov_b32_e32 v167, v165
	s_xor_b64 exec, exec, s[30:31]
	v_add_u32_e32 v167, 1, v165
	s_or_b64 exec, exec, s[30:31]
	v_add_f32_e32 v169, v169, v176
	v_add_f32_e32 v169, 0, v169
	v_ashrrev_i32_e32 v175, 31, v169
	v_bitop3_b32 v169, v175, v169, s82 bitop3:0x36
	v_lshrrev_b32_e32 v175, 22, v169
	v_cmp_le_i32_e32 vcc, v175, v103
	s_and_saveexec_b64 s[30:31], vcc
	s_xor_b64 s[30:31], exec, s[30:31]
	s_cbranch_execz .LBB0_2679
	v_sub_u32_e32 v175, v175, v102
	v_cmp_lt_i32_e32 vcc, -1, v175
	s_and_saveexec_b64 s[38:39], vcc
	s_cbranch_execz .LBB0_2678
	v_lshrrev_b32_e32 v169, v115, v169
	v_and_b32_e32 v169, v169, v116
	v_lshl_or_b32 v169, v175, v112, v169
	v_lshlrev_b32_e32 v175, 1, v169
	v_and_b32_e32 v175, -4, v175
	v_lshlrev_b32_e32 v169, 4, v169
	v_add_u32_e32 v175, v123, v175
	v_lshlrev_b32_e64 v169, v169, 1
	ds_add_u32 v175, v169 offset:2048

; DI void phase_index(const Params& p, unsigned char* lds) {
;     ...
;             const int key = k0 + 32 * kb + r32;
; #pragma unroll
;             for (int qq = 0; qq < 2; ++qq) {
;                 const float t_lo = tot[qq], t_hi = tot[2 + qq];
;                 const float sc = ((lane & 32) ? t_hi : t_lo) + 0.0f;
;                 const unsigned ub = __float_as_uint(sc);
;                 const unsigned uk = ub ^ ((unsigned)((int)ub >> 31) | 0x80000000u);
;                 const bool valid = DIAG ? (key <= tq0 + qq) : true;
;                 if (PASS == 0) {
;                     if (valid) { const unsigned a = (uk >> 21) & 0x7feu; atomicAdd((unsigned*)(lds + hbase0 + qq * 2048 + (a & ~3u)), 1u << ((a & 2u) << 3)); }
;                 } else if (PASS == 1) {
;                     if (valid && (int)(uk >> 22) == b1v[qq]) { const unsigned a = (uk >> 11) & 0x7feu; atomicAdd((unsigned*)(lds + hbase0 + qq * 2048 + (a & ~3u)), 1u << ((a & 2u) << 3)); }
;                 } else if (PASS == 3) {
;                     if (valid) {
;                         const int k10 = (int)(uk >> 22), d = k10 - b1v[qq];
;                         if (k10 > hiv[qq]) cntA[qq] += 1;
;                         else if (d >= 0) {
;                             const unsigned bin = ((unsigned)d << sbv[qq]) | ((uk >> (22 - sbv[qq])) & ((1u << sbv[qq]) - 1u));
;                             const unsigned a = bin << 1;
;                             atomicAdd((unsigned*)(lds + hbase0 + qq * 2048 + (a & ~3u)), 1u << ((a & 2u) << 3));
;                         }
;                     }
.LBB0_2682:
	v_mov_b32_e32 v167, v170
	v_mov_b32_e32 v169, v172
	s_nop 0
	v_permlane32_swap_b32_e32 v170, v167
	v_permlane32_swap_b32_e32 v173, v174
	v_permlane32_swap_b32_e32 v172, v169
	v_cmp_le_i32_e32 vcc, v164, v95
	s_and_saveexec_b64 s[30:31], vcc
	s_cbranch_execz .LBB0_2690
	v_add_f32_e32 v173, v173, v174
	v_add_f32_e32 v173, 0, v173
	v_ashrrev_i32_e32 v174, 31, v173
	v_bitop3_b32 v173, v174, v173, s82 bitop3:0x36
	v_lshrrev_b32_e32 v174, 22, v173
	v_cmp_le_i32_e32 vcc, v174, v101
	s_and_saveexec_b64 s[34:35], vcc
	s_xor_b64 s[38:39], exec, s[34:35]
	s_cbranch_execz .LBB0_2687
	v_sub_u32_e32 v174, v174, v100
	v_cmp_lt_i32_e32 vcc, -1, v174
	s_and_saveexec_b64 s[50:51], vcc
	s_cbranch_execz .LBB0_2686
	v_lshrrev_b32_e32 v173, v113, v173
	v_and_b32_e32 v173, v173, v114
	v_lshl_or_b32 v173, v174, v111, v173
	v_lshlrev_b32_e32 v174, 1, v173
	v_and_b32_e32 v174, -4, v174
	v_lshlrev_b32_e32 v173, 4, v173
	v_add_u32_e32 v174, v123, v174
	v_lshlrev_b32_e64 v173, v173, 1
	ds_add_u32 v174, v173

; DI float xhalf_sum(float v) { const auto r = __builtin_amdgcn_permlane32_swap(__float_as_uint(v), __float_as_uint(v), false, false); return __uint_as_float(r[0]) + __uint_as_float(r[1]); }
; DI void phase_index(const Params& p, unsigned char* lds) {
;     ...
;             for (int q = 0; q < 4; ++q) {
;                 float pr = 0.f;
; #pragma unroll
;                 for (int e = 0; e < 4; ++e) pr += wq[q][e] * fmaxf(s[4 * q + e], 0.f);
;                 tot[q] = xhalf_sum(pr);
;             }
;             const int key = k0 + 32 * kb + r32;
; #pragma unroll
;             for (int qq = 0; qq < 2; ++qq) {
;                 const float t_lo = tot[qq], t_hi = tot[2 + qq];
;                 const float sc = ((lane & 32) ? t_hi : t_lo) + 0.0f;
;                 const unsigned ub = __float_as_uint(sc);
;                 const unsigned uk = ub ^ ((unsigned)((int)ub >> 31) | 0x80000000u);
;                 const bool valid = DIAG ? (key <= tq0 + qq) : true;
;                 if (PASS == 0) {
;                     if (valid) { const unsigned a = (uk >> 21) & 0x7feu; atomicAdd((unsigned*)(lds + hbase0 + qq * 2048 + (a & ~3u)), 1u << ((a & 2u) << 3)); }
.LBB0_2969:
	v_max_f32_e32 v114, 0, v114
	v_max_f32_e32 v111, 0, v111
	v_max_f32_e32 v106, 0, v106
	v_fma_f32 v114, v54, v114, 0
	v_max_f32_e32 v115, 0, v115
	v_fma_f32 v111, v58, v111, 0
	v_max_f32_e32 v110, 0, v110
	v_fma_f32 v106, v62, v106, 0
	v_max_f32_e32 v105, 0, v105
	v_fmac_f32_e32 v114, v55, v115
	v_max_f32_e32 v113, 0, v113
	v_fmac_f32_e32 v111, v59, v110
	v_max_f32_e32 v109, 0, v109
	v_fmac_f32_e32 v106, v63, v105
	v_max_f32_e32 v104, 0, v104
	v_fmac_f32_e32 v114, v56, v113
	v_max_f32_e32 v112, 0, v112
	v_fmac_f32_e32 v111, v60, v109
	v_max_f32_e32 v108, 0, v108
	v_fmac_f32_e32 v106, v64, v104
	v_max_f32_e32 v103, 0, v103
	v_fmac_f32_e32 v114, v57, v112
	v_fmac_f32_e32 v111, v61, v108
	v_fmac_f32_e32 v106, v65, v103
	s_nop 0
	v_permlane32_swap_b32_e32 v102, v111
	s_nop 0
	v_permlane32_swap_b32_e32 v114, v106
	v_cmp_le_i32_e32 vcc, v101, v95
	s_and_saveexec_b64 s[50:51], vcc
	s_cbranch_execz .LBB0_2971
	v_add_f32_e32 v102, v102, v111
	v_add_f32_e32 v102, 0, v102
	v_ashrrev_i32_e32 v104, 31, v102
	v_bitop3_b32 v102, v104, v102, s82 bitop3:0x36
	v_lshrrev_b32_e32 v104, 21, v102
	v_lshrrev_b32_e32 v102, 18, v102
	v_and_b32_e32 v104, 0x7fc, v104
	v_and_b32_e32 v102, 16, v102
	v_add_u32_e32 v104, v123, v104
	v_lshlrev_b32_e64 v102, v102, 1
	ds_add_u32 v104, v102
.LBB0_2971:
	s_or_b64 exec, exec, s[50:51]
	v_cmp_le_i32_e32 vcc, v101, v1
	s_and_saveexec_b64 s[50:51], vcc
	v_add_f32_e32 v116, v114, v106
	s_or_b64 s[38:39], s[38:39], exec
	s_or_b64 exec, exec, s[50:51]

; DI float xhalf_sum(float v) { const auto r = __builtin_amdgcn_permlane32_swap(__float_as_uint(v), __float_as_uint(v), false, false); return __uint_as_float(r[0]) + __uint_as_float(r[1]); }
; DI void phase_index(const Params& p, unsigned char* lds) {
;     ...
;             for (int q = 0; q < 4; ++q) {
;                 float pr = 0.f;
; #pragma unroll
;                 for (int e = 0; e < 4; ++e) pr += wq[q][e] * fmaxf(s[4 * q + e], 0.f);
;                 tot[q] = xhalf_sum(pr);
;             }
;             const int key = k0 + 32 * kb + r32;
; #pragma unroll
;             for (int qq = 0; qq < 2; ++qq) {
;                 const float t_lo = tot[qq], t_hi = tot[2 + qq];
;                 const float sc = ((lane & 32) ? t_hi : t_lo) + 0.0f;
;                 const unsigned ub = __float_as_uint(sc);
;                 const unsigned uk = ub ^ ((unsigned)((int)ub >> 31) | 0x80000000u);
;                 const bool valid = DIAG ? (key <= tq0 + qq) : true;
;                 if (PASS == 0) {
;                     if (valid) { const unsigned a = (uk >> 21) & 0x7feu; atomicAdd((unsigned*)(lds + hbase0 + qq * 2048 + (a & ~3u)), 1u << ((a & 2u) << 3)); }
.LBB0_2977:
	v_max_f32_e32 v18, 0, v18
	v_fma_f32 v18, v50, v18, 0
	v_max_f32_e32 v19, 0, v19
	v_fmac_f32_e32 v18, v51, v19
	v_max_f32_e32 v19, 0, v20
	v_fmac_f32_e32 v18, v52, v19
	v_max_f32_e32 v19, 0, v21
	v_fmac_f32_e32 v18, v53, v19
	s_and_b64 vcc, exec, s[30:31]
	v_max_f32_e32 v105, v22, v22
	v_max_f32_e32 v104, v23, v23
	v_max_f32_e32 v103, v24, v24
	v_max_f32_e32 v102, v25, v25
	v_max_f32_e32 v26, v26, v26
	v_max_f32_e32 v25, v27, v27
	v_max_f32_e32 v24, v28, v28
	v_max_f32_e32 v23, v29, v29
	v_max_f32_e32 v22, v30, v30
	v_max_f32_e32 v21, v31, v31
	v_max_f32_e32 v20, v32, v32
	v_max_f32_e32 v19, v33, v33
	s_cbranch_vccz .LBB0_2980
	v_mov_b32_e32 v27, v18
	s_nop 1
	v_max_f32_e32 v28, 0, v105
	v_max_f32_e32 v29, 0, v104
	v_pk_mul_f32 v[28:29], v[54:55], v[28:29]
	s_nop 0
	v_add_f32_e32 v28, 0, v28
	v_add_f32_e32 v30, v29, v28
	v_max_f32_e32 v28, 0, v103
	v_max_f32_e32 v29, 0, v102
	v_pk_mul_f32 v[28:29], v[56:57], v[28:29]
	s_mov_b64 s[30:31], -1
	v_add_f32_e32 v28, v28, v30
	v_add_f32_e32 v28, v29, v28
	v_mov_b32_e32 v29, v28
	s_nop 1
	v_permlane32_swap_b32_e32 v28, v29
	v_add_f32_e32 v30, v28, v29
	v_max_f32_e32 v28, 0, v26
	v_fma_f32 v28, v58, v28, 0
	v_max_f32_e32 v29, 0, v25
	v_fmac_f32_e32 v28, v59, v29
	v_max_f32_e32 v29, 0, v24
	v_fmac_f32_e32 v28, v60, v29
	v_max_f32_e32 v29, 0, v23
	v_fmac_f32_e32 v28, v61, v29
	s_nop 1
	v_permlane32_swap_b32_e32 v27, v28
	v_add_f32_e32 v27, v27, v28
	v_max_f32_e32 v28, 0, v22
	v_max_f32_e32 v29, 0, v21
	v_add_f32_e32 v27, 0, v27
	v_pk_mul_f32 v[28:29], v[62:63], v[28:29]
	v_ashrrev_i32_e32 v31, 31, v27
	v_add_f32_e32 v28, 0, v28
	v_bitop3_b32 v27, v31, v27, s82 bitop3:0x36
	v_add_f32_e32 v32, v29, v28
	v_max_f32_e32 v28, 0, v20
	v_max_f32_e32 v29, 0, v19
	v_lshrrev_b32_e32 v31, 21, v27
	v_lshrrev_b32_e32 v27, 18, v27
	v_pk_mul_f32 v[28:29], v[64:65], v[28:29]
	v_and_b32_e32 v31, 0x7fc, v31
	v_and_b32_e32 v27, 16, v27
	v_add_f32_e32 v28, v28, v32
	v_add_u32_e32 v31, v123, v31
	v_lshlrev_b32_e64 v27, v27, 1
	v_add_f32_e32 v28, v29, v28
	ds_add_u32 v31, v27
	v_mov_b32_e32 v29, v28
	s_nop 1
	v_permlane32_swap_b32_e32 v28, v29
	v_add_f32_e32 v27, v28, v29
	v_cndmask_b32_e64 v29, v27, v30, s[4:5]
	s_cbranch_execz .LBB0_2981
	s_branch .LBB0_2986

; DI void phase_index(const Params& p, unsigned char* lds) {
;     ...
;             const int key = k0 + 32 * kb + r32;
; #pragma unroll
;             for (int qq = 0; qq < 2; ++qq) {
;                 const float t_lo = tot[qq], t_hi = tot[2 + qq];
;                 const float sc = ((lane & 32) ? t_hi : t_lo) + 0.0f;
;                 const unsigned ub = __float_as_uint(sc);
;                 const unsigned uk = ub ^ ((unsigned)((int)ub >> 31) | 0x80000000u);
;                 const bool valid = DIAG ? (key <= tq0 + qq) : true;
;                 if (PASS == 0) {
;                     if (valid) { const unsigned a = (uk >> 21) & 0x7feu; atomicAdd((unsigned*)(lds + hbase0 + qq * 2048 + (a & ~3u)), 1u << ((a & 2u) << 3)); }
.LBB0_2981:
	v_max_f32_e32 v27, 0, v105
	v_max_f32_e32 v26, 0, v26
	v_max_f32_e32 v22, 0, v22
	v_fma_f32 v27, v54, v27, 0
	v_max_f32_e32 v28, 0, v104
	v_fma_f32 v26, v58, v26, 0
	v_max_f32_e32 v25, 0, v25
	v_fma_f32 v22, v62, v22, 0
	v_max_f32_e32 v21, 0, v21
	v_fmac_f32_e32 v27, v55, v28
	v_max_f32_e32 v28, 0, v103
	v_fmac_f32_e32 v26, v59, v25
	v_max_f32_e32 v24, 0, v24
	v_fmac_f32_e32 v22, v63, v21
	v_max_f32_e32 v20, 0, v20
	v_fmac_f32_e32 v27, v56, v28
	v_max_f32_e32 v28, 0, v102
	v_fmac_f32_e32 v26, v60, v24
	v_max_f32_e32 v23, 0, v23
	v_fmac_f32_e32 v22, v64, v20
	v_max_f32_e32 v19, 0, v19
	v_fmac_f32_e32 v27, v57, v28
	v_fmac_f32_e32 v26, v61, v23
	v_fmac_f32_e32 v22, v65, v19
	v_add_u32_e32 v20, 32, v101
	v_permlane32_swap_b32_e32 v18, v26
	v_permlane32_swap_b32_e32 v27, v22
	v_cmp_le_i32_e32 vcc, v20, v95
	s_and_saveexec_b64 s[38:39], vcc
	s_cbranch_execz .LBB0_2983
	v_add_f32_e32 v18, v18, v26
	v_add_f32_e32 v18, 0, v18
	v_ashrrev_i32_e32 v20, 31, v18
	v_bitop3_b32 v18, v20, v18, s82 bitop3:0x36
	v_lshrrev_b32_e32 v20, 21, v18
	v_lshrrev_b32_e32 v18, 18, v18
	v_and_b32_e32 v20, 0x7fc, v20
	v_and_b32_e32 v18, 16, v18
	v_add_u32_e32 v20, v123, v20
	v_lshlrev_b32_e64 v18, v18, 1
	ds_add_u32 v20, v18
.LBB0_2983:
	s_or_b64 exec, exec, s[38:39]
	v_add_u32_e32 v18, 31, v101
	v_cmp_le_i32_e32 vcc, v18, v95
	s_and_saveexec_b64 s[38:39], vcc
	v_add_f32_e32 v29, v27, v22
	s_or_b64 s[30:31], s[30:31], exec
	s_or_b64 exec, exec, s[38:39]

; #define MFMA32(a, b, c) __builtin_amdgcn_mfma_f32_32x32x16_bf16((a), (b), (c), 0, 0, 0)
; DI float xhalf_sum(float v) { const auto r = __builtin_amdgcn_permlane32_swap(__float_as_uint(v), __float_as_uint(v), false, false); return __uint_as_float(r[0]) + __uint_as_float(r[1]); }
; DI void phase_index(const Params& p, unsigned char* lds) {
;     ...
;         auto mma = [&](f32x16& s, unsigned off) {
; #pragma unroll
;             for (int i = 0; i < 16; ++i) s[i] = 0.f;
; #pragma unroll
;             for (int ks = 0; ks < 4; ++ks) { const bf16x8 kf = *(const bf16x8*)(lds + off + ks * 32); s = MFMA32(qf[ks], kf, s); }
;         };
;         auto proc = [&](auto PASSC, auto DIAGC, const f32x16& s, int k0, int kb) {
;             constexpr int PASS = decltype(PASSC)::value; constexpr bool DIAG = decltype(DIAGC)::value != 0;
;             f32x4 tot;
; #pragma unroll
;             for (int q = 0; q < 4; ++q) {
;                 float pr = 0.f;
; #pragma unroll
;                 for (int e = 0; e < 4; ++e) pr += wq[q][e] * fmaxf(s[4 * q + e], 0.f);
;                 tot[q] = xhalf_sum(pr);
;             }
;             const int key = k0 + 32 * kb + r32;
; #pragma unroll
;             for (int qq = 0; qq < 2; ++qq) {
;                 const float t_lo = tot[qq], t_hi = tot[2 + qq];
;                 const float sc = ((lane & 32) ? t_hi : t_lo) + 0.0f;
;                 const unsigned ub = __float_as_uint(sc);
;                 const unsigned uk = ub ^ ((unsigned)((int)ub >> 31) | 0x80000000u);
;                 const bool valid = DIAG ? (key <= tq0 + qq) : true;
;                 if (PASS == 0) {
;                     if (valid) { const unsigned a = (uk >> 21) & 0x7feu; atomicAdd((unsigned*)(lds + hbase0 + qq * 2048 + (a & ~3u)), 1u << ((a & 2u) << 3)); }
;                 } else if (PASS == 1) {
;                     if (valid && (int)(uk >> 22) == b1v[qq]) { const unsigned a = (uk >> 11) & 0x7feu; atomicAdd((unsigned*)(lds + hbase0 + qq * 2048 + (a & ~3u)), 1u << ((a & 2u) << 3)); }
.LBB0_3242:
	v_add_u32_e32 v115, s50, v113
	v_add_u32_e32 v18, 0x11200, v115
	ds_read_b128 v[18:21], v18
	v_add_u32_e32 v22, 0x11220, v115
	ds_read_b128 v[162:165], v22
	v_add_u32_e32 v167, 0x11240, v115
	s_waitcnt lgkmcnt(1)
	v_mfma_f32_32x32x16_bf16 v[18:33], v[42:45], v[18:21], 0
	v_max_f32_e32 v116, 0, v2
	v_max_f32_e32 v170, v6, v6
	v_max_f32_e32 v173, 0, v3
	v_fma_f32 v117, v50, v116, 0
	v_max_f32_e32 v172, v7, v7
	s_waitcnt lgkmcnt(0)
	v_mfma_f32_32x32x16_bf16 v[18:33], v[34:37], v[162:165], v[18:33]
	ds_read_b128 v[162:165], v167
	v_max_f32_e32 v161, 0, v4
	v_fmac_f32_e32 v117, v51, v173
	v_fmac_f32_e32 v117, v52, v161
	v_max_f32_e32 v161, 0, v8
	s_waitcnt lgkmcnt(0)
	v_mfma_f32_32x32x16_bf16 v[18:33], v[38:41], v[162:165], v[18:33]
	v_max_f32_e32 v162, 0, v170
	v_max_f32_e32 v163, 0, v172
	v_fma_f32 v116, v54, v162, 0
	v_fmac_f32_e32 v116, v55, v163
	v_fmac_f32_e32 v116, v56, v161
	v_max_f32_e32 v161, 0, v9
	v_fmac_f32_e32 v116, v57, v161
	v_max_f32_e32 v161, 0, v10
	v_add_u32_e32 v168, 0x11260, v115
	v_fma_f32 v162, v58, v161, 0
	v_max_f32_e32 v174, 0, v5
	ds_read_b128 v[166:169], v168
	v_max_f32_e32 v161, 0, v11
	v_fmac_f32_e32 v162, v59, v161
	v_max_f32_e32 v161, 0, v12
	v_fmac_f32_e32 v162, v60, v161
	v_max_f32_e32 v161, 0, v13
	s_waitcnt lgkmcnt(0)
	v_mfma_f32_32x32x16_bf16 v[18:33], v[46:49], v[166:169], v[18:33]
	v_fmac_f32_e32 v162, v61, v161
	v_max_f32_e32 v161, 0, v14
	v_fma_f32 v161, v62, v161, 0
	v_max_f32_e32 v163, 0, v15
	v_fmac_f32_e32 v161, v63, v163
	v_max_f32_e32 v163, 0, v16
	s_cmp_lg_u32 s0, s51
	v_fmac_f32_e32 v161, v64, v163
	s_cselect_b64 s[30:31], -1, 0
	v_max_f32_e32 v163, 0, v17
	v_fmac_f32_e32 v117, v53, v174
	v_fmac_f32_e32 v161, v65, v163
	s_and_b64 vcc, exec, s[30:31]
	s_cbranch_vccz .LBB0_3246
	v_mov_b32_e32 v163, v117
	v_mov_b32_e32 v165, v162
	s_nop 0
	s_nop 0
	v_permlane32_swap_b32_e32 v163, v165
	v_add_f32_e32 v167, v163, v165
	v_add_f32_e32 v167, 0, v167
	v_ashrrev_i32_e32 v168, 31, v167
	v_bitop3_b32 v167, v168, v167, s82 bitop3:0x36
	v_mov_b32_e32 v163, v116
	v_mov_b32_e32 v165, v161
	v_lshrrev_b32_e32 v168, 22, v167
	s_nop 0
	v_permlane32_swap_b32_e32 v163, v165
	v_cmp_eq_u32_e32 vcc, v168, v108
	s_and_saveexec_b64 s[26:27], vcc
	s_cbranch_execz .LBB0_3245
	v_lshrrev_b32_e32 v168, 11, v167
	v_lshrrev_b32_e32 v167, 8, v167
	v_and_b32_e32 v168, 0x7fc, v168
	v_and_b32_e32 v167, 16, v167
	v_add_u32_e32 v168, v123, v168
	v_lshlrev_b32_e64 v167, v167, 1
	ds_add_u32 v168, v167
.LBB0_3245:
	s_or_b64 exec, exec, s[26:27]
	v_add_f32_e32 v163, v163, v165
	v_add_f32_e32 v163, 0, v163
	v_ashrrev_i32_e32 v164, 31, v163
	v_bitop3_b32 v163, v164, v163, s82 bitop3:0x36
	v_lshrrev_b32_e32 v164, 22, v163
	v_cmp_eq_u32_e64 s[26:27], v164, v109
	s_branch .LBB0_3251
.LBB0_3246:
	s_mov_b64 s[26:27], 0
	s_cbranch_execz .LBB0_3251
	v_permlane32_swap_b32_e32 v117, v162
	v_permlane32_swap_b32_e32 v116, v161
	v_cmp_le_i32_e32 vcc, v114, v95
	s_and_saveexec_b64 s[26:27], vcc
	s_cbranch_execz .LBB0_3250
	v_add_f32_e32 v117, v117, v162
	v_add_f32_e32 v117, 0, v117
	v_ashrrev_i32_e32 v162, 31, v117
	v_bitop3_b32 v117, v162, v117, s82 bitop3:0x36
	v_lshrrev_b32_e32 v162, 22, v117
	v_cmp_eq_u32_e32 vcc, v162, v108
	s_and_b64 exec, exec, vcc
	s_cbranch_execz .LBB0_3250
	v_lshrrev_b32_e32 v162, 11, v117
	v_lshrrev_b32_e32 v117, 8, v117
	v_and_b32_e32 v162, 0x7fc, v162
	v_and_b32_e32 v117, 16, v117
	v_add_u32_e32 v162, v123, v162
	v_lshlrev_b32_e64 v117, v117, 1
	ds_add_u32 v162, v117
.LBB0_3250:
	s_or_b64 exec, exec, s[26:27]
	v_add_f32_e32 v116, v116, v161
	v_add_f32_e32 v116, 0, v116
	v_ashrrev_i32_e32 v117, 31, v116
	v_bitop3_b32 v163, v117, v116, s82 bitop3:0x36
	v_lshrrev_b32_e32 v116, 22, v163
	v_cmp_le_i32_e32 vcc, v114, v110
	v_cmp_eq_u32_e64 s[26:27], v116, v109
	s_and_b64 s[26:27], vcc, s[26:27]

; DI float xhalf_sum(float v) { const auto r = __builtin_amdgcn_permlane32_swap(__float_as_uint(v), __float_as_uint(v), false, false); return __uint_as_float(r[0]) + __uint_as_float(r[1]); }
; DI void phase_index(const Params& p, unsigned char* lds) {
;     ...
;             for (int q = 0; q < 4; ++q) {
;                 float pr = 0.f;
; #pragma unroll
;                 for (int e = 0; e < 4; ++e) pr += wq[q][e] * fmaxf(s[4 * q + e], 0.f);
;                 tot[q] = xhalf_sum(pr);
;             }
;             const int key = k0 + 32 * kb + r32;
; #pragma unroll
;             for (int qq = 0; qq < 2; ++qq) {
;                 const float t_lo = tot[qq], t_hi = tot[2 + qq];
;                 const float sc = ((lane & 32) ? t_hi : t_lo) + 0.0f;
;                 const unsigned ub = __float_as_uint(sc);
;                 const unsigned uk = ub ^ ((unsigned)((int)ub >> 31) | 0x80000000u);
;                 const bool valid = DIAG ? (key <= tq0 + qq) : true;
;                 if (PASS == 0) {
;                     if (valid) { const unsigned a = (uk >> 21) & 0x7feu; atomicAdd((unsigned*)(lds + hbase0 + qq * 2048 + (a & ~3u)), 1u << ((a & 2u) << 3)); }
;                 } else if (PASS == 1) {
;                     if (valid && (int)(uk >> 22) == b1v[qq]) { const unsigned a = (uk >> 11) & 0x7feu; atomicAdd((unsigned*)(lds + hbase0 + qq * 2048 + (a & ~3u)), 1u << ((a & 2u) << 3)); }
.LBB0_3254:
	v_max_f32_e32 v18, 0, v18
	v_fma_f32 v115, v50, v18, 0
	v_max_f32_e32 v18, 0, v19
	v_fmac_f32_e32 v115, v51, v18
	v_max_f32_e32 v18, 0, v20
	v_fmac_f32_e32 v115, v52, v18
	v_max_f32_e32 v18, 0, v21
	v_fmac_f32_e32 v115, v53, v18
	v_max_f32_e32 v18, 0, v22
	v_fma_f32 v18, v54, v18, 0
	v_max_f32_e32 v19, 0, v23
	v_fmac_f32_e32 v18, v55, v19
	v_max_f32_e32 v19, 0, v24
	v_fmac_f32_e32 v18, v56, v19
	v_max_f32_e32 v19, 0, v25
	v_fmac_f32_e32 v18, v57, v19
	v_max_f32_e32 v19, 0, v26
	v_fma_f32 v20, v58, v19, 0
	v_max_f32_e32 v19, 0, v27
	v_fmac_f32_e32 v20, v59, v19
	v_max_f32_e32 v19, 0, v28
	v_fmac_f32_e32 v20, v60, v19
	v_max_f32_e32 v19, 0, v29
	v_fmac_f32_e32 v20, v61, v19
	v_max_f32_e32 v19, 0, v30
	v_fma_f32 v19, v62, v19, 0
	v_max_f32_e32 v21, 0, v31
	v_fmac_f32_e32 v19, v63, v21
	v_max_f32_e32 v21, 0, v32
	v_fmac_f32_e32 v19, v64, v21
	v_max_f32_e32 v21, 0, v33
	v_fmac_f32_e32 v19, v65, v21
	s_and_b64 vcc, exec, s[30:31]
	s_cbranch_vccz .LBB0_3259
	v_mov_b32_e32 v21, v115
	v_mov_b32_e32 v23, v20
	s_nop 0
	s_nop 0
	v_permlane32_swap_b32_e32 v21, v23
	v_add_f32_e32 v25, v21, v23
	v_add_f32_e32 v25, 0, v25
	v_ashrrev_i32_e32 v26, 31, v25
	v_bitop3_b32 v25, v26, v25, s82 bitop3:0x36
	v_mov_b32_e32 v21, v18
	v_mov_b32_e32 v23, v19
	v_lshrrev_b32_e32 v26, 22, v25
	s_nop 0
	v_permlane32_swap_b32_e32 v21, v23
	v_cmp_eq_u32_e32 vcc, v26, v108
	s_and_saveexec_b64 s[26:27], vcc
	s_cbranch_execz .LBB0_3257
	v_lshrrev_b32_e32 v26, 11, v25
	v_lshrrev_b32_e32 v25, 8, v25
	v_and_b32_e32 v26, 0x7fc, v26
	v_and_b32_e32 v25, 16, v25
	v_add_u32_e32 v26, v123, v26
	v_lshlrev_b32_e64 v25, v25, 1
	ds_add_u32 v26, v25
.LBB0_3257:
	s_or_b64 exec, exec, s[26:27]
	v_add_f32_e32 v21, v21, v23
	v_add_f32_e32 v21, 0, v21
	v_ashrrev_i32_e32 v22, 31, v21
	v_bitop3_b32 v21, v22, v21, s82 bitop3:0x36
	v_lshrrev_b32_e32 v22, 22, v21
	v_cmp_eq_u32_e64 s[26:27], v22, v109
	s_branch .LBB0_3264

; DI void phase_index(const Params& p, unsigned char* lds) {
;     ...
;             const int key = k0 + 32 * kb + r32;
; #pragma unroll
;             for (int qq = 0; qq < 2; ++qq) {
;                 const float t_lo = tot[qq], t_hi = tot[2 + qq];
;                 const float sc = ((lane & 32) ? t_hi : t_lo) + 0.0f;
;                 const unsigned ub = __float_as_uint(sc);
;                 const unsigned uk = ub ^ ((unsigned)((int)ub >> 31) | 0x80000000u);
;                 const bool valid = DIAG ? (key <= tq0 + qq) : true;
;                 if (PASS == 0) {
;                     if (valid) { const unsigned a = (uk >> 21) & 0x7feu; atomicAdd((unsigned*)(lds + hbase0 + qq * 2048 + (a & ~3u)), 1u << ((a & 2u) << 3)); }
;                 } else if (PASS == 1) {
;                     if (valid && (int)(uk >> 22) == b1v[qq]) { const unsigned a = (uk >> 11) & 0x7feu; atomicAdd((unsigned*)(lds + hbase0 + qq * 2048 + (a & ~3u)), 1u << ((a & 2u) << 3)); }
.LBB0_3259:
	s_mov_b64 s[26:27], 0
	s_cbranch_execz .LBB0_3264
	v_add_u32_e32 v25, 32, v114
	v_permlane32_swap_b32_e32 v115, v20
	v_permlane32_swap_b32_e32 v18, v19
	v_cmp_le_i32_e32 vcc, v25, v95
	s_and_saveexec_b64 s[26:27], vcc
	s_cbranch_execz .LBB0_3263
	v_add_f32_e32 v20, v115, v20
	v_add_f32_e32 v20, 0, v20
	v_ashrrev_i32_e32 v23, 31, v20
	v_bitop3_b32 v20, v23, v20, s82 bitop3:0x36
	v_lshrrev_b32_e32 v23, 22, v20
	v_cmp_eq_u32_e32 vcc, v23, v108
	s_and_b64 exec, exec, vcc
	s_cbranch_execz .LBB0_3263
	v_lshrrev_b32_e32 v23, 11, v20
	v_lshrrev_b32_e32 v20, 8, v20
	v_and_b32_e32 v23, 0x7fc, v23
	v_and_b32_e32 v20, 16, v20
	v_add_u32_e32 v23, v123, v23
	v_lshlrev_b32_e64 v20, v20, 1
	ds_add_u32 v23, v20
.LBB0_3263:
	s_or_b64 exec, exec, s[26:27]
	v_add_f32_e32 v18, v18, v19
	v_add_f32_e32 v18, 0, v18
	v_ashrrev_i32_e32 v19, 31, v18
	v_bitop3_b32 v21, v19, v18, s82 bitop3:0x36
	v_add_u32_e32 v18, 31, v114
	v_cmp_le_i32_e32 vcc, v18, v95
	v_lshrrev_b32_e32 v18, 22, v21
	v_cmp_eq_u32_e64 s[26:27], v18, v109
	s_and_b64 s[26:27], vcc, s[26:27]

; DI void phase_index(const Params& p, unsigned char* lds) {
;     ...
;             for (int q = 0; q < 4; ++q) {
;                 float pr = 0.f;
; #pragma unroll
;                 for (int e = 0; e < 4; ++e) pr += wq[q][e] * fmaxf(s[4 * q + e], 0.f);
;                 tot[q] = xhalf_sum(pr);
;             }
;             const int key = k0 + 32 * kb + r32;
; #pragma unroll
;             for (int qq = 0; qq < 2; ++qq) {
;                 const float t_lo = tot[qq], t_hi = tot[2 + qq];
;                 const float sc = ((lane & 32) ? t_hi : t_lo) + 0.0f;
;                 const unsigned ub = __float_as_uint(sc);
;                 const unsigned uk = ub ^ ((unsigned)((int)ub >> 31) | 0x80000000u);
;                 const bool valid = DIAG ? (key <= tq0 + qq) : true;
;                 if (PASS == 0) {
;                     if (valid) { const unsigned a = (uk >> 21) & 0x7feu; atomicAdd((unsigned*)(lds + hbase0 + qq * 2048 + (a & ~3u)), 1u << ((a & 2u) << 3)); }
;                 } else if (PASS == 1) {
;                     if (valid && (int)(uk >> 22) == b1v[qq]) { const unsigned a = (uk >> 11) & 0x7feu; atomicAdd((unsigned*)(lds + hbase0 + qq * 2048 + (a & ~3u)), 1u << ((a & 2u) << 3)); }
;                 } else if (PASS == 3) {
;                     if (valid) {
;                         const int k10 = (int)(uk >> 22), d = k10 - b1v[qq];
;                         if (k10 > hiv[qq]) cntA[qq] += 1;
;                         else if (d >= 0) {
;                             const unsigned bin = ((unsigned)d << sbv[qq]) | ((uk >> (22 - sbv[qq])) & ((1u << sbv[qq]) - 1u));
;                             const unsigned a = bin << 1;
;                             atomicAdd((unsigned*)(lds + hbase0 + qq * 2048 + (a & ~3u)), 1u << ((a & 2u) << 3));
;                         }
;                     }
;                 } else {
;                     const int k20 = (int)(uk >> kshv[qq]);
;                     const u64 bg = __ballot(valid && k20 > tauv[qq]);
;                     const u64 be = __ballot(valid && k20 == tauv[qq]);
;                     Gm[qq] |= (bg & 0xffffffffull) << (32 * kb); Gm[2 + qq] |= (bg >> 32) << (32 * kb);
;                     Em[qq] |= (be & 0xffffffffull) << (32 * kb); Em[2 + qq] |= (be >> 32) << (32 * kb);
;                 }
.LBB0_3524:
	v_max_f32_e32 v18, 0, v18
	v_fma_f32 v18, v50, v18, 0
	v_max_f32_e32 v19, 0, v19
	v_fmac_f32_e32 v18, v51, v19
	v_max_f32_e32 v19, 0, v20
	v_fmac_f32_e32 v18, v52, v19
	v_max_f32_e32 v19, 0, v21
	v_fmac_f32_e32 v18, v53, v19
	v_max_f32_e32 v19, 0, v22
	v_fma_f32 v19, v54, v19, 0
	v_max_f32_e32 v20, 0, v23
	v_fmac_f32_e32 v19, v55, v20
	v_max_f32_e32 v20, 0, v24
	v_fmac_f32_e32 v19, v56, v20
	v_max_f32_e32 v20, 0, v25
	v_fmac_f32_e32 v19, v57, v20
	v_max_f32_e32 v20, 0, v26
	v_fma_f32 v20, v58, v20, 0
	v_max_f32_e32 v21, 0, v27
	v_fmac_f32_e32 v20, v59, v21
	v_max_f32_e32 v21, 0, v28
	v_fmac_f32_e32 v20, v60, v21
	v_max_f32_e32 v21, 0, v29
	v_fmac_f32_e32 v20, v61, v21
	v_max_f32_e32 v21, 0, v30
	v_fma_f32 v21, v62, v21, 0
	v_max_f32_e32 v22, 0, v31
	v_fmac_f32_e32 v21, v63, v22
	v_max_f32_e32 v22, 0, v32
	v_fmac_f32_e32 v21, v64, v22
	v_max_f32_e32 v22, 0, v33
	v_fmac_f32_e32 v21, v65, v22
	s_mov_b64 s[28:29], -1
	s_and_b64 vcc, exec, s[58:59]
	s_cbranch_vccz .LBB0_3526
	v_mov_b32_e32 v22, v18
	v_mov_b32_e32 v23, v19
	v_mov_b32_e32 v26, v20
	v_mov_b32_e32 v27, v21
	s_nop 0
	v_permlane32_swap_b32_e32 v22, v26
	s_nop 0
	v_permlane32_swap_b32_e32 v23, v27
	v_pk_add_f32 v[22:23], v[22:23], v[26:27]
	s_mov_b64 s[28:29], 0
	v_pk_add_f32 v[22:23], v[22:23], 0 op_sel_hi:[1,0]
	s_nop 0
	v_ashrrev_i32_e32 v24, 31, v23
	v_ashrrev_i32_e32 v25, 31, v22
	v_or_b32_e32 v24, 0x80000000, v24
	v_or_b32_e32 v25, 0x80000000, v25
	v_xor_b32_e32 v23, v24, v23
	v_xor_b32_e32 v22, v25, v22
	v_lshrrev_b32_e32 v23, v83, v23
	v_lshrrev_b32_e32 v22, v106, v22
	v_cmp_gt_i32_e64 s[58:59], v22, v100
	v_cmp_eq_u32_e64 s[68:69], v22, v100
	v_cmp_gt_i32_e64 s[30:31], v23, v1
	v_cmp_eq_u32_e64 s[26:27], v23, v1

; DI void phase_index(const Params& p, unsigned char* lds) {
;     ...
;             for (int q = 0; q < 4; ++q) {
;                 float pr = 0.f;
; #pragma unroll
;                 for (int e = 0; e < 4; ++e) pr += wq[q][e] * fmaxf(s[4 * q + e], 0.f);
;                 tot[q] = xhalf_sum(pr);
;             }
;             const int key = k0 + 32 * kb + r32;
; #pragma unroll
;             for (int qq = 0; qq < 2; ++qq) {
;                 const float t_lo = tot[qq], t_hi = tot[2 + qq];
;                 const float sc = ((lane & 32) ? t_hi : t_lo) + 0.0f;
;                 const unsigned ub = __float_as_uint(sc);
;                 const unsigned uk = ub ^ ((unsigned)((int)ub >> 31) | 0x80000000u);
;                 const bool valid = DIAG ? (key <= tq0 + qq) : true;
;                 if (PASS == 0) {
;                     if (valid) { const unsigned a = (uk >> 21) & 0x7feu; atomicAdd((unsigned*)(lds + hbase0 + qq * 2048 + (a & ~3u)), 1u << ((a & 2u) << 3)); }
;                 } else if (PASS == 1) {
;                     if (valid && (int)(uk >> 22) == b1v[qq]) { const unsigned a = (uk >> 11) & 0x7feu; atomicAdd((unsigned*)(lds + hbase0 + qq * 2048 + (a & ~3u)), 1u << ((a & 2u) << 3)); }
;                 } else if (PASS == 3) {
;                     if (valid) {
;                         const int k10 = (int)(uk >> 22), d = k10 - b1v[qq];
;                         if (k10 > hiv[qq]) cntA[qq] += 1;
;                         else if (d >= 0) {
;                             const unsigned bin = ((unsigned)d << sbv[qq]) | ((uk >> (22 - sbv[qq])) & ((1u << sbv[qq]) - 1u));
;                             const unsigned a = bin << 1;
;                             atomicAdd((unsigned*)(lds + hbase0 + qq * 2048 + (a & ~3u)), 1u << ((a & 2u) << 3));
;                         }
;                     }
;                 } else {
;                     const int k20 = (int)(uk >> kshv[qq]);
;                     const u64 bg = __ballot(valid && k20 > tauv[qq]);
;                     const u64 be = __ballot(valid && k20 == tauv[qq]);
;                     Gm[qq] |= (bg & 0xffffffffull) << (32 * kb); Gm[2 + qq] |= (bg >> 32) << (32 * kb);
;                     Em[qq] |= (be & 0xffffffffull) << (32 * kb); Em[2 + qq] |= (be >> 32) << (32 * kb);
;                 }
.LBB0_3555:
	v_mov_b32_e32 v164, v114
	v_mov_b32_e32 v165, v115
	v_mov_b32_e32 v168, v116
	v_mov_b32_e32 v169, v117
	s_nop 0
	v_permlane32_swap_b32_e32 v164, v168
	s_nop 0
	v_permlane32_swap_b32_e32 v165, v169
	v_pk_add_f32 v[164:165], v[164:165], v[168:169]
	s_nop 0
	v_pk_add_f32 v[164:165], v[164:165], 0 op_sel_hi:[1,0]
	s_nop 0
	v_ashrrev_i32_e32 v166, 31, v165
	v_ashrrev_i32_e32 v167, 31, v164
	v_or_b32_e32 v166, 0x80000000, v166
	v_or_b32_e32 v167, 0x80000000, v167
	v_xor_b32_e32 v165, v166, v165
	v_xor_b32_e32 v164, v167, v164
	v_lshrrev_b32_e32 v165, v83, v165
	v_lshrrev_b32_e32 v164, v106, v164
	v_cmp_gt_i32_e64 s[52:53], v164, v100
	v_cmp_eq_u32_e64 s[56:57], v164, v100
	v_cmp_gt_i32_e64 s[50:51], v165, v1
	v_cmp_eq_u32_e64 s[54:55], v165, v1
	s_lshl_b32 s28, s36, 6
	v_or_b32_e32 v164, s28, v194
	s_cbranch_execnz .LBB0_3522
